# v52 + up-phase second epilogue (waves 4-7 block): 32 serialized sig(mb) gate loads pipelined 3 deep via SGPR row base + lane offset + immediate column offset
# baseline (speedup 1.0000x reference)
; DI float bflo(unsigned u) { return __uint_as_float(u << 16); }
; DI float bfhi(unsigned u) { return __uint_as_float(u & 0xffff0000u); }
; DI float sigmoidf(float x) { return __builtin_amdgcn_rcpf(1.f + __expf(-x)); }
; template <class F>
; DI void gemm8_epi_staged(f32x4 (&acc)[8][4], int m0, int n0, bf16_t* L0, F f, bf16_t* dst, size_t ld, int nmax) {
;     ...
;     if (wm == half) {
; #pragma unroll
;       for (int i = 0; i < 8; ++i)
; #pragma unroll
;         for (int j = 0; j < 4; ++j) {
;           const int ml = i * 16 + (lane & 15);
;           const int nl = wn * 64 + j * 16 + (lane >> 4) * 4;
;           f32x4 a = acc[i][j];
;           f(m0 + half * 128 + ml, n0 + nl, a);
;           uint2 u;
;           u.x = pack2(a[0], a[1]);
;           u.y = pack2(a[2], a[3]);
;           *(uint2*)(L + ml * 264 + nl) = u;
;         }
;     }
;     __syncthreads();
; #pragma unroll
;     for (int it = 0; it < 8; ++it) {
;       const int idx = tid + 512 * it;
;       const int row = idx >> 5, ch = idx & 31;
;       const u32x4 v = *(const u32x4*)(L + row * 264 + ch * 8);
;       const int n = n0 + ch * 8;
;       if (n < nmax) *(u32x4*)(dst + (size_t)(m0 + half * 128 + row) * ld + n) = v;
;     }
; __global__ void __launch_bounds__(512, 2) mega(Params p) {
;     ...
;       gemm8_epi_staged(acc8, m0, n0, lds_all, [&](int m, int n, f32x4& a) {
;         uint2 ub = *(const uint2*)(z + (size_t)m * ZS + C_MB + n);
;         a[0] *= sigmoidf(bflo(ub.x)); a[1] *= sigmoidf(bfhi(ub.x));
;         a[2] *= sigmoidf(bflo(ub.y)); a[3] *= sigmoidf(bfhi(ub.y));
;       }, z + C_RK, ZS, 1024);
.LBB0_783:
	s_or_b64 exec, exec, s[0:1]
	v_lshlrev_b32_e32 v0, 3, v140
	v_and_b32_e32 v0, 0xf8, v0
	v_or_b32_e32 v131, s12, v0
	v_readlane_b32 s0, v252, 43
	v_lshl_add_u32 v158, v0, 1, s20
	v_lshlrev_b32_e32 v0, 1, v131
	v_readlane_b32 s1, v252, 44
	v_ashrrev_i32_e32 v136, 5, v140
	s_movk_i32 s6, 0x210
	v_lshl_add_u64 v[132:133], s[0:1], 0, v[0:1]
	v_mul_lo_u32 v0, v136, s6
	v_add_u32_e32 v141, v158, v0
	s_waitcnt lgkmcnt(0)
	s_barrier
	ds_read_b128 v[142:145], v141
	v_add_u32_e32 v0, s13, v136
	v_mad_i64_i32 v[134:135], s[0:1], v0, s35, v[132:133]
	v_add_u32_e32 v0, 0x200, v140
	v_ashrrev_i32_e32 v137, 5, v0
	v_mul_lo_u32 v0, v137, s6
	s_waitcnt lgkmcnt(0)
	global_store_dwordx4 v[134:135], v[142:145], off
	s_nop 1
	v_add_u32_e32 v142, v158, v0
	ds_read_b128 v[144:147], v142
	v_add_u32_e32 v0, s13, v137
	v_mad_i64_i32 v[134:135], s[0:1], v0, s35, v[132:133]
	v_add_u32_e32 v0, 0x400, v140
	v_ashrrev_i32_e32 v143, 5, v0
	v_mul_lo_u32 v0, v143, s6
	s_waitcnt lgkmcnt(0)
	global_store_dwordx4 v[134:135], v[144:147], off
	s_nop 1
	v_add_u32_e32 v145, v158, v0
	ds_read_b128 v[146:149], v145
	v_add_u32_e32 v0, s13, v143
	v_mad_i64_i32 v[134:135], s[0:1], v0, s35, v[132:133]
	v_add_u32_e32 v0, 0x600, v140
	v_ashrrev_i32_e32 v144, 5, v0
	v_mul_lo_u32 v0, v144, s6
	s_waitcnt lgkmcnt(0)
	global_store_dwordx4 v[134:135], v[146:149], off
	s_nop 1
	v_add_u32_e32 v146, v158, v0
	ds_read_b128 v[148:151], v146
	v_add_u32_e32 v0, s13, v144
	v_mad_i64_i32 v[134:135], s[0:1], v0, s35, v[132:133]
	v_add_u32_e32 v0, 0x800, v140
	v_ashrrev_i32_e32 v147, 5, v0
	v_mul_lo_u32 v0, v147, s6
	s_waitcnt lgkmcnt(0)
	global_store_dwordx4 v[134:135], v[148:151], off
	s_nop 1
	v_add_u32_e32 v149, v158, v0
	ds_read_b128 v[150:153], v149
	v_add_u32_e32 v0, s13, v147
	v_mad_i64_i32 v[134:135], s[0:1], v0, s35, v[132:133]
	v_add_u32_e32 v0, 0xa00, v140
	v_ashrrev_i32_e32 v148, 5, v0
	v_mul_lo_u32 v0, v148, s6
	s_waitcnt lgkmcnt(0)
	global_store_dwordx4 v[134:135], v[150:153], off
	s_nop 1
	v_add_u32_e32 v150, v158, v0
	ds_read_b128 v[152:155], v150
	v_add_u32_e32 v0, s13, v148
	v_mad_i64_i32 v[134:135], s[0:1], v0, s35, v[132:133]
	v_add_u32_e32 v0, 0xc00, v140
	v_ashrrev_i32_e32 v151, 5, v0
	v_mul_lo_u32 v0, v151, s6
	s_waitcnt lgkmcnt(0)
	global_store_dwordx4 v[134:135], v[152:155], off
	s_nop 1
	v_add_u32_e32 v153, v158, v0
	ds_read_b128 v[154:157], v153
	v_add_u32_e32 v0, s13, v151
	v_mad_i64_i32 v[134:135], s[0:1], v0, s35, v[132:133]
	v_add_u32_e32 v0, 0xe00, v140
	v_ashrrev_i32_e32 v152, 5, v0
	v_mul_lo_u32 v0, v152, s6
	s_waitcnt lgkmcnt(0)
	global_store_dwordx4 v[134:135], v[154:157], off
	s_nop 1
	v_add_u32_e32 v154, v158, v0
	ds_read_b128 v[156:159], v154
	v_add_u32_e32 v0, s13, v152
	v_mad_i64_i32 v[134:135], s[0:1], v0, s35, v[132:133]
	v_and_b32_e32 v0, 0xffffff00, v140
	s_movk_i32 s0, 0x100
	v_cmp_eq_u32_e32 vcc, s0, v0
	s_bitset1_b32 s13, 7
	s_waitcnt lgkmcnt(0)
	global_store_dwordx4 v[134:135], v[156:159], off
	s_barrier
	s_and_saveexec_b64 s[0:1], vcc
	s_cbranch_execz .LBB0_772
	v_or_b32_e32 v139, s13, v139
	v_mul_u32_u24_e32 v0, 0x2a30, v139
	v_lshl_add_u64 v[134:135], s[16:17], 0, v[0:1]
	s_mov_b64 s[6:7], 0x2230
	v_lshl_add_u64 v[134:135], v[134:135], 0, s[6:7]
	v_mov_b32_e32 v131, v1
	v_lshl_add_u64 v[156:157], v[134:135], 0, v[130:131]
	s_nop 0
	v_readfirstlane_b32 s86, v156
	v_readfirstlane_b32 s87, v157
	s_sub_u32 s86, s86, 0x40000000
	s_subb_u32 s87, s87, 0
	v_subrev_u32_e32 v163, s86, v156
	global_load_dwordx2 v[160:161], v163, s[86:87]
	global_load_dwordx2 v[188:189], v163, s[86:87] offset:32
	global_load_dwordx2 v[190:191], v163, s[86:87] offset:64
	s_waitcnt vmcnt(2)
	v_mov_b64_e32 v[156:157], v[160:161]
	global_load_dwordx2 v[160:161], v163, s[86:87] offset:96
	v_lshlrev_b32_e32 v0, 16, v156
	v_mul_f32_e32 v0, 0xbfb8aa3b, v0
	v_exp_f32_e32 v0, v0
	s_nop 0
	v_add_f32_e32 v0, 1.0, v0
	v_rcp_f32_e32 v158, v0
	v_and_b32_e32 v0, 0xffff0000, v156
	v_mul_f32_e32 v0, 0xbfb8aa3b, v0
	v_exp_f32_e32 v0, v0
	s_nop 0
	v_add_f32_e32 v0, 1.0, v0
	v_rcp_f32_e32 v159, v0
	v_lshlrev_b32_e32 v0, 16, v157
	v_mul_f32_e32 v0, 0xbfb8aa3b, v0
	v_exp_f32_e32 v0, v0
	v_pk_mul_f32 v[126:127], v[126:127], v[158:159]
	v_add_f32_e32 v0, 1.0, v0
	v_rcp_f32_e32 v156, v0
	v_and_b32_e32 v0, 0xffff0000, v157
	v_mul_f32_e32 v0, 0xbfb8aa3b, v0
	v_exp_f32_e32 v0, v0
	v_cvt_pk_bf16_f32 v126, v126, v127
	v_add_f32_e32 v0, 1.0, v0
	v_rcp_f32_e32 v157, v0
	v_or_b32_e32 v0, 32, v130
	v_pk_mul_f32 v[128:129], v[128:129], v[156:157]
	s_nop 0
	v_cvt_pk_bf16_f32 v127, v128, v129
	v_lshl_add_u64 v[128:129], v[134:135], 0, v[0:1]
	s_waitcnt vmcnt(2)
	v_mov_b64_e32 v[128:129], v[188:189]
	s_add_u32 s86, s86, 0x2a300
	s_addc_u32 s87, s87, 0
	global_load_dwordx2 v[188:189], v163, s[86:87]
	v_lshlrev_b32_e32 v140, 16, v128
	v_and_b32_e32 v128, 0xffff0000, v128
	v_mul_f32_e32 v128, 0xbfb8aa3b, v128
	v_exp_f32_e32 v128, v128
	v_mul_f32_e32 v140, 0xbfb8aa3b, v140
	v_exp_f32_e32 v140, v140
	v_add_f32_e32 v128, 1.0, v128
	v_rcp_f32_e32 v157, v128
	v_lshlrev_b32_e32 v128, 16, v129
	v_and_b32_e32 v129, 0xffff0000, v129
	v_mul_f32_e32 v128, 0xbfb8aa3b, v128
	v_mul_f32_e32 v129, 0xbfb8aa3b, v129
	v_exp_f32_e32 v128, v128
	v_exp_f32_e32 v129, v129
	v_add_f32_e32 v140, 1.0, v140
	v_rcp_f32_e32 v156, v140
	v_add_f32_e32 v128, 1.0, v128
	v_add_f32_e32 v129, 1.0, v129
	v_rcp_f32_e32 v128, v128
	v_rcp_f32_e32 v129, v129
	v_pk_mul_f32 v[122:123], v[122:123], v[156:157]
	v_pk_mul_f32 v[124:125], v[124:125], v[128:129]
	v_cvt_pk_bf16_f32 v122, v122, v123
	v_cvt_pk_bf16_f32 v123, v124, v125
	ds_write2_b64 v138, v[126:127], v[122:123] offset1:4
	v_or_b32_e32 v122, 64, v130
	v_mov_b32_e32 v123, v1
	v_lshl_add_u64 v[124:125], v[134:135], 0, v[122:123]
	s_waitcnt vmcnt(2)
; DI float bflo(unsigned u) { return __uint_as_float(u << 16); }
; DI float bfhi(unsigned u) { return __uint_as_float(u & 0xffff0000u); }
; DI float sigmoidf(float x) { return __builtin_amdgcn_rcpf(1.f + __expf(-x)); }
; template <class F>
; DI void gemm8_epi_staged(f32x4 (&acc)[8][4], int m0, int n0, bf16_t* L0, F f, bf16_t* dst, size_t ld, int nmax) {
;     ...
;     if (wm == half) {
; #pragma unroll
;       for (int i = 0; i < 8; ++i)
; #pragma unroll
;         for (int j = 0; j < 4; ++j) {
;           const int ml = i * 16 + (lane & 15);
;           const int nl = wn * 64 + j * 16 + (lane >> 4) * 4;
;           f32x4 a = acc[i][j];
;           f(m0 + half * 128 + ml, n0 + nl, a);
;           uint2 u;
;           u.x = pack2(a[0], a[1]);
;           u.y = pack2(a[2], a[3]);
;           *(uint2*)(L + ml * 264 + nl) = u;
;         }
;     }
; __global__ void __launch_bounds__(512, 2) mega(Params p) {
;     ...
;       gemm8_epi_staged(acc8, m0, n0, lds_all, [&](int m, int n, f32x4& a) {
;         uint2 ub = *(const uint2*)(z + (size_t)m * ZS + C_MB + n);
;         a[0] *= sigmoidf(bflo(ub.x)); a[1] *= sigmoidf(bfhi(ub.x));
;         a[2] *= sigmoidf(bflo(ub.y)); a[3] *= sigmoidf(bfhi(ub.y));
;       }, z + C_RK, ZS, 1024);
	v_mov_b64_e32 v[124:125], v[190:191]
	global_load_dwordx2 v[190:191], v163, s[86:87] offset:32
	v_lshlrev_b32_e32 v126, 16, v124
	v_and_b32_e32 v124, 0xffff0000, v124
	v_mul_f32_e32 v124, 0xbfb8aa3b, v124
	v_exp_f32_e32 v124, v124
	v_mul_f32_e32 v126, 0xbfb8aa3b, v126
	v_exp_f32_e32 v126, v126
	v_add_f32_e32 v124, 1.0, v124
	v_rcp_f32_e32 v127, v124
	v_lshlrev_b32_e32 v124, 16, v125
	v_and_b32_e32 v125, 0xffff0000, v125
	v_mul_f32_e32 v124, 0xbfb8aa3b, v124
	v_mul_f32_e32 v125, 0xbfb8aa3b, v125
	v_exp_f32_e32 v124, v124
	v_exp_f32_e32 v125, v125
	v_add_f32_e32 v126, 1.0, v126
	v_rcp_f32_e32 v126, v126
	v_add_f32_e32 v124, 1.0, v124
	v_add_f32_e32 v125, 1.0, v125
	v_rcp_f32_e32 v124, v124
	v_rcp_f32_e32 v125, v125
	v_pk_mul_f32 v[118:119], v[118:119], v[126:127]
	v_pk_mul_f32 v[120:121], v[120:121], v[124:125]
	v_cvt_pk_bf16_f32 v124, v118, v119
	v_or_b32_e32 v118, 0x60, v130
	v_mov_b32_e32 v119, v1
	v_cvt_pk_bf16_f32 v125, v120, v121
	v_lshl_add_u64 v[120:121], v[134:135], 0, v[118:119]
	s_waitcnt vmcnt(2)
	v_mov_b64_e32 v[120:121], v[160:161]
	global_load_dwordx2 v[160:161], v163, s[86:87] offset:64
	v_lshlrev_b32_e32 v126, 16, v120
	v_and_b32_e32 v120, 0xffff0000, v120
	v_mul_f32_e32 v120, 0xbfb8aa3b, v120
	v_exp_f32_e32 v120, v120
	v_mul_f32_e32 v126, 0xbfb8aa3b, v126
	v_exp_f32_e32 v126, v126
	v_add_f32_e32 v120, 1.0, v120
	v_rcp_f32_e32 v127, v120
	v_lshlrev_b32_e32 v120, 16, v121
	v_and_b32_e32 v121, 0xffff0000, v121
	v_mul_f32_e32 v120, 0xbfb8aa3b, v120
	v_mul_f32_e32 v121, 0xbfb8aa3b, v121
	v_exp_f32_e32 v120, v120
	v_exp_f32_e32 v121, v121
	v_add_f32_e32 v126, 1.0, v126
	v_rcp_f32_e32 v126, v126
	v_add_f32_e32 v120, 1.0, v120
	v_add_f32_e32 v121, 1.0, v121
	v_rcp_f32_e32 v120, v120
	v_rcp_f32_e32 v121, v121
	v_pk_mul_f32 v[114:115], v[114:115], v[126:127]
	v_pk_mul_f32 v[116:117], v[116:117], v[120:121]
	v_cvt_pk_bf16_f32 v114, v114, v115
	v_cvt_pk_bf16_f32 v115, v116, v117
	ds_write2_b64 v138, v[124:125], v[114:115] offset0:8 offset1:12
	v_or_b32_e32 v114, 16, v139
	v_mul_u32_u24_e32 v114, 0x2a30, v114
	v_mov_b32_e32 v115, v1
	v_lshl_add_u64 v[114:115], s[16:17], 0, v[114:115]
	v_lshl_add_u64 v[114:115], v[114:115], 0, s[6:7]
	v_lshl_add_u64 v[116:117], v[114:115], 0, v[130:131]
	s_waitcnt vmcnt(2)
	v_mov_b64_e32 v[116:117], v[188:189]
	global_load_dwordx2 v[188:189], v163, s[86:87] offset:96
	v_lshlrev_b32_e32 v120, 16, v116
	v_and_b32_e32 v116, 0xffff0000, v116
	v_mul_f32_e32 v116, 0xbfb8aa3b, v116
	v_exp_f32_e32 v116, v116
	v_mul_f32_e32 v120, 0xbfb8aa3b, v120
	v_exp_f32_e32 v120, v120
	v_add_f32_e32 v116, 1.0, v116
	v_rcp_f32_e32 v121, v116
	v_lshlrev_b32_e32 v116, 16, v117
	v_and_b32_e32 v117, 0xffff0000, v117
	v_mul_f32_e32 v116, 0xbfb8aa3b, v116
	v_mul_f32_e32 v117, 0xbfb8aa3b, v117
	v_exp_f32_e32 v116, v116
	v_exp_f32_e32 v117, v117
	v_add_f32_e32 v120, 1.0, v120
	v_rcp_f32_e32 v120, v120
	v_add_f32_e32 v116, 1.0, v116
	v_add_f32_e32 v117, 1.0, v117
	v_rcp_f32_e32 v116, v116
	v_rcp_f32_e32 v117, v117
	v_pk_mul_f32 v[110:111], v[110:111], v[120:121]
	v_pk_mul_f32 v[112:113], v[112:113], v[116:117]
	v_cvt_pk_bf16_f32 v110, v110, v111
	v_cvt_pk_bf16_f32 v111, v112, v113
	v_lshl_add_u64 v[112:113], v[114:115], 0, v[0:1]
	s_waitcnt vmcnt(2)
	v_mov_b64_e32 v[112:113], v[190:191]
	s_add_u32 s86, s86, 0x2a300
	s_addc_u32 s87, s87, 0
	global_load_dwordx2 v[190:191], v163, s[86:87]
	v_lshlrev_b32_e32 v116, 16, v112
	v_and_b32_e32 v112, 0xffff0000, v112
	v_mul_f32_e32 v112, 0xbfb8aa3b, v112
	v_exp_f32_e32 v112, v112
	v_mul_f32_e32 v116, 0xbfb8aa3b, v116
	v_exp_f32_e32 v116, v116
	v_add_f32_e32 v112, 1.0, v112
	v_rcp_f32_e32 v117, v112
	v_lshlrev_b32_e32 v112, 16, v113
	v_and_b32_e32 v113, 0xffff0000, v113
	v_mul_f32_e32 v112, 0xbfb8aa3b, v112
	v_mul_f32_e32 v113, 0xbfb8aa3b, v113
	v_exp_f32_e32 v112, v112
	v_exp_f32_e32 v113, v113
	v_add_f32_e32 v116, 1.0, v116
	v_rcp_f32_e32 v116, v116
	v_add_f32_e32 v112, 1.0, v112
	v_add_f32_e32 v113, 1.0, v113
	v_rcp_f32_e32 v112, v112
	v_rcp_f32_e32 v113, v113
	v_pk_mul_f32 v[106:107], v[106:107], v[116:117]
	v_pk_mul_f32 v[108:109], v[108:109], v[112:113]
	s_nop 0
	v_cvt_pk_bf16_f32 v113, v108, v109
	v_lshl_add_u64 v[108:109], v[114:115], 0, v[122:123]
	s_waitcnt vmcnt(2)
	v_mov_b64_e32 v[108:109], v[160:161]
	global_load_dwordx2 v[160:161], v163, s[86:87] offset:32
	v_cvt_pk_bf16_f32 v112, v106, v107
	v_add_u32_e32 v106, 0x2000, v138
	ds_write2_b64 v106, v[110:111], v[112:113] offset0:32 offset1:36
	v_lshlrev_b32_e32 v107, 16, v108
	v_mul_f32_e32 v107, 0xbfb8aa3b, v107
	v_exp_f32_e32 v107, v107
	s_nop 0
	v_add_f32_e32 v107, 1.0, v107
	v_rcp_f32_e32 v110, v107
	v_and_b32_e32 v107, 0xffff0000, v108
	v_mul_f32_e32 v107, 0xbfb8aa3b, v107
	v_exp_f32_e32 v107, v107
	s_nop 0
	v_add_f32_e32 v107, 1.0, v107
	v_rcp_f32_e32 v111, v107
	v_lshlrev_b32_e32 v107, 16, v109
	v_mul_f32_e32 v107, 0xbfb8aa3b, v107
	v_exp_f32_e32 v107, v107
	v_pk_mul_f32 v[102:103], v[102:103], v[110:111]
	v_add_f32_e32 v107, 1.0, v107
	v_rcp_f32_e32 v108, v107
	v_and_b32_e32 v107, 0xffff0000, v109
	v_mul_f32_e32 v107, 0xbfb8aa3b, v107
	v_exp_f32_e32 v107, v107
	v_cvt_pk_bf16_f32 v102, v102, v103
	v_add_f32_e32 v107, 1.0, v107
	v_rcp_f32_e32 v109, v107
	s_nop 0
	v_pk_mul_f32 v[104:105], v[104:105], v[108:109]
	s_nop 0
	v_cvt_pk_bf16_f32 v103, v104, v105
	v_lshl_add_u64 v[104:105], v[114:115], 0, v[118:119]
	s_waitcnt vmcnt(2)
; DI float bflo(unsigned u) { return __uint_as_float(u << 16); }
; DI float bfhi(unsigned u) { return __uint_as_float(u & 0xffff0000u); }
; DI float sigmoidf(float x) { return __builtin_amdgcn_rcpf(1.f + __expf(-x)); }
; template <class F>
; DI void gemm8_epi_staged(f32x4 (&acc)[8][4], int m0, int n0, bf16_t* L0, F f, bf16_t* dst, size_t ld, int nmax) {
;     ...
;     if (wm == half) {
; #pragma unroll
;       for (int i = 0; i < 8; ++i)
; #pragma unroll
;         for (int j = 0; j < 4; ++j) {
;           const int ml = i * 16 + (lane & 15);
;           const int nl = wn * 64 + j * 16 + (lane >> 4) * 4;
;           f32x4 a = acc[i][j];
;           f(m0 + half * 128 + ml, n0 + nl, a);
;           uint2 u;
;           u.x = pack2(a[0], a[1]);
;           u.y = pack2(a[2], a[3]);
;           *(uint2*)(L + ml * 264 + nl) = u;
;         }
;     }
; __global__ void __launch_bounds__(512, 2) mega(Params p) {
;     ...
;       gemm8_epi_staged(acc8, m0, n0, lds_all, [&](int m, int n, f32x4& a) {
;         uint2 ub = *(const uint2*)(z + (size_t)m * ZS + C_MB + n);
;         a[0] *= sigmoidf(bflo(ub.x)); a[1] *= sigmoidf(bfhi(ub.x));
;         a[2] *= sigmoidf(bflo(ub.y)); a[3] *= sigmoidf(bfhi(ub.y));
;       }, z + C_RK, ZS, 1024);
	v_mov_b64_e32 v[104:105], v[188:189]
	global_load_dwordx2 v[188:189], v163, s[86:87] offset:64
	v_lshlrev_b32_e32 v107, 16, v104
	v_and_b32_e32 v104, 0xffff0000, v104
	v_mul_f32_e32 v104, 0xbfb8aa3b, v104
	v_exp_f32_e32 v104, v104
	v_mul_f32_e32 v107, 0xbfb8aa3b, v107
	v_exp_f32_e32 v107, v107
	v_add_f32_e32 v104, 1.0, v104
	v_rcp_f32_e32 v109, v104
	v_lshlrev_b32_e32 v104, 16, v105
	v_and_b32_e32 v105, 0xffff0000, v105
	v_mul_f32_e32 v104, 0xbfb8aa3b, v104
	v_mul_f32_e32 v105, 0xbfb8aa3b, v105
	v_exp_f32_e32 v104, v104
	v_exp_f32_e32 v105, v105
	v_add_f32_e32 v107, 1.0, v107
	v_rcp_f32_e32 v108, v107
	v_add_f32_e32 v104, 1.0, v104
	v_add_f32_e32 v105, 1.0, v105
	v_rcp_f32_e32 v104, v104
	v_rcp_f32_e32 v105, v105
	v_pk_mul_f32 v[98:99], v[98:99], v[108:109]
	v_pk_mul_f32 v[100:101], v[100:101], v[104:105]
	v_cvt_pk_bf16_f32 v98, v98, v99
	v_cvt_pk_bf16_f32 v99, v100, v101
	ds_write2_b64 v106, v[102:103], v[98:99] offset0:40 offset1:44
	v_or_b32_e32 v98, 32, v139
	v_mul_u32_u24_e32 v98, 0x2a30, v98
	v_mov_b32_e32 v99, v1
	v_lshl_add_u64 v[98:99], s[16:17], 0, v[98:99]
	v_lshl_add_u64 v[98:99], v[98:99], 0, s[6:7]
	v_lshl_add_u64 v[100:101], v[98:99], 0, v[130:131]
	s_waitcnt vmcnt(2)
	v_mov_b64_e32 v[100:101], v[190:191]
	global_load_dwordx2 v[190:191], v163, s[86:87] offset:96
	v_lshlrev_b32_e32 v102, 16, v100
	v_and_b32_e32 v100, 0xffff0000, v100
	v_mul_f32_e32 v100, 0xbfb8aa3b, v100
	v_exp_f32_e32 v100, v100
	v_mul_f32_e32 v102, 0xbfb8aa3b, v102
	v_exp_f32_e32 v102, v102
	v_add_f32_e32 v100, 1.0, v100
	v_rcp_f32_e32 v103, v100
	v_lshlrev_b32_e32 v100, 16, v101
	v_and_b32_e32 v101, 0xffff0000, v101
	v_mul_f32_e32 v100, 0xbfb8aa3b, v100
	v_mul_f32_e32 v101, 0xbfb8aa3b, v101
	v_exp_f32_e32 v100, v100
	v_exp_f32_e32 v101, v101
	v_add_f32_e32 v102, 1.0, v102
	v_rcp_f32_e32 v102, v102
	v_add_f32_e32 v100, 1.0, v100
	v_add_f32_e32 v101, 1.0, v101
	v_rcp_f32_e32 v100, v100
	v_rcp_f32_e32 v101, v101
	v_pk_mul_f32 v[94:95], v[94:95], v[102:103]
	v_pk_mul_f32 v[96:97], v[96:97], v[100:101]
	v_cvt_pk_bf16_f32 v94, v94, v95
	v_cvt_pk_bf16_f32 v95, v96, v97
	v_lshl_add_u64 v[96:97], v[98:99], 0, v[0:1]
	s_waitcnt vmcnt(2)
	v_mov_b64_e32 v[96:97], v[160:161]
	s_add_u32 s86, s86, 0x2a300
	s_addc_u32 s87, s87, 0
	global_load_dwordx2 v[160:161], v163, s[86:87]
	v_lshlrev_b32_e32 v100, 16, v96
	v_and_b32_e32 v96, 0xffff0000, v96
	v_mul_f32_e32 v96, 0xbfb8aa3b, v96
	v_exp_f32_e32 v96, v96
	v_mul_f32_e32 v100, 0xbfb8aa3b, v100
	v_exp_f32_e32 v100, v100
	v_add_f32_e32 v96, 1.0, v96
	v_rcp_f32_e32 v101, v96
	v_lshlrev_b32_e32 v96, 16, v97
	v_and_b32_e32 v97, 0xffff0000, v97
	v_mul_f32_e32 v96, 0xbfb8aa3b, v96
	v_mul_f32_e32 v97, 0xbfb8aa3b, v97
	v_exp_f32_e32 v96, v96
	v_exp_f32_e32 v97, v97
	v_add_f32_e32 v100, 1.0, v100
	v_rcp_f32_e32 v100, v100
	v_add_f32_e32 v96, 1.0, v96
	v_add_f32_e32 v97, 1.0, v97
	v_rcp_f32_e32 v96, v96
	v_rcp_f32_e32 v97, v97
	v_pk_mul_f32 v[90:91], v[90:91], v[100:101]
	v_pk_mul_f32 v[92:93], v[92:93], v[96:97]
	v_cvt_pk_bf16_f32 v90, v90, v91
	v_cvt_pk_bf16_f32 v91, v92, v93
	v_add_u32_e32 v96, 0x4000, v138
	ds_write2_b64 v96, v[94:95], v[90:91] offset0:64 offset1:68
	v_lshl_add_u64 v[90:91], v[98:99], 0, v[122:123]
	s_waitcnt vmcnt(2)
	v_mov_b64_e32 v[90:91], v[188:189]
	global_load_dwordx2 v[188:189], v163, s[86:87] offset:32
	v_lshlrev_b32_e32 v92, 16, v90
	v_and_b32_e32 v90, 0xffff0000, v90
	v_mul_f32_e32 v90, 0xbfb8aa3b, v90
	v_exp_f32_e32 v90, v90
	v_mul_f32_e32 v92, 0xbfb8aa3b, v92
	v_exp_f32_e32 v92, v92
	v_add_f32_e32 v90, 1.0, v90
	v_rcp_f32_e32 v93, v90
	v_lshlrev_b32_e32 v90, 16, v91
	v_and_b32_e32 v91, 0xffff0000, v91
	v_mul_f32_e32 v90, 0xbfb8aa3b, v90
	v_mul_f32_e32 v91, 0xbfb8aa3b, v91
	v_exp_f32_e32 v90, v90
	v_exp_f32_e32 v91, v91
	v_add_f32_e32 v92, 1.0, v92
	v_rcp_f32_e32 v92, v92
	v_add_f32_e32 v90, 1.0, v90
	v_add_f32_e32 v91, 1.0, v91
	v_rcp_f32_e32 v90, v90
	v_rcp_f32_e32 v91, v91
	v_pk_mul_f32 v[86:87], v[86:87], v[92:93]
	v_pk_mul_f32 v[88:89], v[88:89], v[90:91]
	v_cvt_pk_bf16_f32 v86, v86, v87
	v_cvt_pk_bf16_f32 v87, v88, v89
	v_lshl_add_u64 v[88:89], v[98:99], 0, v[118:119]
	s_waitcnt vmcnt(2)
	v_mov_b64_e32 v[88:89], v[190:191]
	global_load_dwordx2 v[190:191], v163, s[86:87] offset:64
	v_lshlrev_b32_e32 v90, 16, v88
	v_and_b32_e32 v88, 0xffff0000, v88
	v_mul_f32_e32 v88, 0xbfb8aa3b, v88
	v_exp_f32_e32 v88, v88
	v_mul_f32_e32 v90, 0xbfb8aa3b, v90
	v_exp_f32_e32 v90, v90
	v_add_f32_e32 v88, 1.0, v88
	v_rcp_f32_e32 v91, v88
	v_lshlrev_b32_e32 v88, 16, v89
	v_and_b32_e32 v89, 0xffff0000, v89
	v_mul_f32_e32 v88, 0xbfb8aa3b, v88
	v_mul_f32_e32 v89, 0xbfb8aa3b, v89
	v_exp_f32_e32 v88, v88
	v_exp_f32_e32 v89, v89
	v_add_f32_e32 v90, 1.0, v90
	v_rcp_f32_e32 v90, v90
	v_add_f32_e32 v88, 1.0, v88
	v_add_f32_e32 v89, 1.0, v89
	v_rcp_f32_e32 v88, v88
	v_rcp_f32_e32 v89, v89
	v_pk_mul_f32 v[82:83], v[82:83], v[90:91]
	v_pk_mul_f32 v[84:85], v[84:85], v[88:89]
	v_cvt_pk_bf16_f32 v82, v82, v83
	v_cvt_pk_bf16_f32 v83, v84, v85
	ds_write2_b64 v96, v[86:87], v[82:83] offset0:72 offset1:76
	v_or_b32_e32 v82, 48, v139
	v_mul_u32_u24_e32 v82, 0x2a30, v82
	v_mov_b32_e32 v83, v1
	v_lshl_add_u64 v[82:83], s[16:17], 0, v[82:83]
	v_lshl_add_u64 v[82:83], v[82:83], 0, s[6:7]
	v_lshl_add_u64 v[84:85], v[82:83], 0, v[130:131]
	s_waitcnt vmcnt(2)
; DI float bflo(unsigned u) { return __uint_as_float(u << 16); }
; DI float bfhi(unsigned u) { return __uint_as_float(u & 0xffff0000u); }
; DI float sigmoidf(float x) { return __builtin_amdgcn_rcpf(1.f + __expf(-x)); }
; template <class F>
; DI void gemm8_epi_staged(f32x4 (&acc)[8][4], int m0, int n0, bf16_t* L0, F f, bf16_t* dst, size_t ld, int nmax) {
;     ...
;     if (wm == half) {
; #pragma unroll
;       for (int i = 0; i < 8; ++i)
; #pragma unroll
;         for (int j = 0; j < 4; ++j) {
;           const int ml = i * 16 + (lane & 15);
;           const int nl = wn * 64 + j * 16 + (lane >> 4) * 4;
;           f32x4 a = acc[i][j];
;           f(m0 + half * 128 + ml, n0 + nl, a);
;           uint2 u;
;           u.x = pack2(a[0], a[1]);
;           u.y = pack2(a[2], a[3]);
;           *(uint2*)(L + ml * 264 + nl) = u;
;         }
;     }
; __global__ void __launch_bounds__(512, 2) mega(Params p) {
;     ...
;       gemm8_epi_staged(acc8, m0, n0, lds_all, [&](int m, int n, f32x4& a) {
;         uint2 ub = *(const uint2*)(z + (size_t)m * ZS + C_MB + n);
;         a[0] *= sigmoidf(bflo(ub.x)); a[1] *= sigmoidf(bfhi(ub.x));
;         a[2] *= sigmoidf(bflo(ub.y)); a[3] *= sigmoidf(bfhi(ub.y));
;       }, z + C_RK, ZS, 1024);
	v_mov_b64_e32 v[84:85], v[160:161]
	global_load_dwordx2 v[160:161], v163, s[86:87] offset:96
	v_lshlrev_b32_e32 v86, 16, v84
	v_and_b32_e32 v84, 0xffff0000, v84
	v_mul_f32_e32 v84, 0xbfb8aa3b, v84
	v_exp_f32_e32 v84, v84
	v_mul_f32_e32 v86, 0xbfb8aa3b, v86
	v_exp_f32_e32 v86, v86
	v_add_f32_e32 v84, 1.0, v84
	v_rcp_f32_e32 v87, v84
	v_lshlrev_b32_e32 v84, 16, v85
	v_and_b32_e32 v85, 0xffff0000, v85
	v_mul_f32_e32 v84, 0xbfb8aa3b, v84
	v_mul_f32_e32 v85, 0xbfb8aa3b, v85
	v_exp_f32_e32 v84, v84
	v_exp_f32_e32 v85, v85
	v_add_f32_e32 v86, 1.0, v86
	v_rcp_f32_e32 v86, v86
	v_add_f32_e32 v84, 1.0, v84
	v_add_f32_e32 v85, 1.0, v85
	v_rcp_f32_e32 v84, v84
	v_rcp_f32_e32 v85, v85
	v_pk_mul_f32 v[78:79], v[78:79], v[86:87]
	v_pk_mul_f32 v[80:81], v[80:81], v[84:85]
	v_cvt_pk_bf16_f32 v78, v78, v79
	v_cvt_pk_bf16_f32 v79, v80, v81
	v_lshl_add_u64 v[80:81], v[82:83], 0, v[0:1]
	s_waitcnt vmcnt(2)
	v_mov_b64_e32 v[80:81], v[188:189]
	s_add_u32 s86, s86, 0x2a300
	s_addc_u32 s87, s87, 0
	global_load_dwordx2 v[188:189], v163, s[86:87]
	v_lshlrev_b32_e32 v84, 16, v80
	v_and_b32_e32 v80, 0xffff0000, v80
	v_mul_f32_e32 v80, 0xbfb8aa3b, v80
	v_exp_f32_e32 v80, v80
	v_mul_f32_e32 v84, 0xbfb8aa3b, v84
	v_exp_f32_e32 v84, v84
	v_add_f32_e32 v80, 1.0, v80
	v_rcp_f32_e32 v85, v80
	v_lshlrev_b32_e32 v80, 16, v81
	v_and_b32_e32 v81, 0xffff0000, v81
	v_mul_f32_e32 v80, 0xbfb8aa3b, v80
	v_mul_f32_e32 v81, 0xbfb8aa3b, v81
	v_exp_f32_e32 v80, v80
	v_exp_f32_e32 v81, v81
	v_add_f32_e32 v84, 1.0, v84
	v_rcp_f32_e32 v84, v84
	v_add_f32_e32 v80, 1.0, v80
	v_add_f32_e32 v81, 1.0, v81
	v_rcp_f32_e32 v80, v80
	v_rcp_f32_e32 v81, v81
	v_pk_mul_f32 v[74:75], v[74:75], v[84:85]
	v_pk_mul_f32 v[76:77], v[76:77], v[80:81]
	v_cvt_pk_bf16_f32 v74, v74, v75
	v_cvt_pk_bf16_f32 v75, v76, v77
	v_add_u32_e32 v80, 0x6000, v138
	ds_write2_b64 v80, v[78:79], v[74:75] offset0:96 offset1:100
	v_lshl_add_u64 v[74:75], v[82:83], 0, v[122:123]
	s_waitcnt vmcnt(2)
	v_mov_b64_e32 v[74:75], v[190:191]
	global_load_dwordx2 v[190:191], v163, s[86:87] offset:32
	v_lshlrev_b32_e32 v76, 16, v74
	v_and_b32_e32 v74, 0xffff0000, v74
	v_mul_f32_e32 v74, 0xbfb8aa3b, v74
	v_exp_f32_e32 v74, v74
	v_mul_f32_e32 v76, 0xbfb8aa3b, v76
	v_exp_f32_e32 v76, v76
	v_add_f32_e32 v74, 1.0, v74
	v_rcp_f32_e32 v77, v74
	v_lshlrev_b32_e32 v74, 16, v75
	v_and_b32_e32 v75, 0xffff0000, v75
	v_mul_f32_e32 v74, 0xbfb8aa3b, v74
	v_mul_f32_e32 v75, 0xbfb8aa3b, v75
	v_exp_f32_e32 v74, v74
	v_exp_f32_e32 v75, v75
	v_add_f32_e32 v76, 1.0, v76
	v_rcp_f32_e32 v76, v76
	v_add_f32_e32 v74, 1.0, v74
	v_add_f32_e32 v75, 1.0, v75
	v_rcp_f32_e32 v74, v74
	v_rcp_f32_e32 v75, v75
	v_pk_mul_f32 v[70:71], v[70:71], v[76:77]
	v_pk_mul_f32 v[72:73], v[72:73], v[74:75]
	v_cvt_pk_bf16_f32 v70, v70, v71
	v_cvt_pk_bf16_f32 v71, v72, v73
	v_lshl_add_u64 v[72:73], v[82:83], 0, v[118:119]
	s_waitcnt vmcnt(2)
	v_mov_b64_e32 v[72:73], v[160:161]
	global_load_dwordx2 v[160:161], v163, s[86:87] offset:64
	v_lshlrev_b32_e32 v74, 16, v72
	v_and_b32_e32 v72, 0xffff0000, v72
	v_mul_f32_e32 v72, 0xbfb8aa3b, v72
	v_exp_f32_e32 v72, v72
	v_mul_f32_e32 v74, 0xbfb8aa3b, v74
	v_exp_f32_e32 v74, v74
	v_add_f32_e32 v72, 1.0, v72
	v_rcp_f32_e32 v75, v72
	v_lshlrev_b32_e32 v72, 16, v73
	v_and_b32_e32 v73, 0xffff0000, v73
	v_mul_f32_e32 v72, 0xbfb8aa3b, v72
	v_mul_f32_e32 v73, 0xbfb8aa3b, v73
	v_exp_f32_e32 v72, v72
	v_exp_f32_e32 v73, v73
	v_add_f32_e32 v74, 1.0, v74
	v_rcp_f32_e32 v74, v74
	v_add_f32_e32 v72, 1.0, v72
	v_add_f32_e32 v73, 1.0, v73
	v_rcp_f32_e32 v72, v72
	v_rcp_f32_e32 v73, v73
	v_pk_mul_f32 v[66:67], v[66:67], v[74:75]
	v_pk_mul_f32 v[68:69], v[68:69], v[72:73]
	v_cvt_pk_bf16_f32 v66, v66, v67
	v_cvt_pk_bf16_f32 v67, v68, v69
	ds_write2_b64 v80, v[70:71], v[66:67] offset0:104 offset1:108
	v_or_b32_e32 v66, 64, v139
	v_mul_u32_u24_e32 v66, 0x2a30, v66
	v_mov_b32_e32 v67, v1
	v_lshl_add_u64 v[66:67], s[16:17], 0, v[66:67]
	v_lshl_add_u64 v[66:67], v[66:67], 0, s[6:7]
	v_lshl_add_u64 v[68:69], v[66:67], 0, v[130:131]
	s_waitcnt vmcnt(2)
	v_mov_b64_e32 v[68:69], v[188:189]
	global_load_dwordx2 v[188:189], v163, s[86:87] offset:96
	v_lshlrev_b32_e32 v70, 16, v68
	v_and_b32_e32 v68, 0xffff0000, v68
	v_mul_f32_e32 v68, 0xbfb8aa3b, v68
	v_exp_f32_e32 v68, v68
	v_mul_f32_e32 v70, 0xbfb8aa3b, v70
	v_exp_f32_e32 v70, v70
	v_add_f32_e32 v68, 1.0, v68
	v_rcp_f32_e32 v71, v68
	v_lshlrev_b32_e32 v68, 16, v69
	v_and_b32_e32 v69, 0xffff0000, v69
	v_mul_f32_e32 v68, 0xbfb8aa3b, v68
	v_mul_f32_e32 v69, 0xbfb8aa3b, v69
	v_exp_f32_e32 v68, v68
	v_exp_f32_e32 v69, v69
	v_add_f32_e32 v70, 1.0, v70
	v_rcp_f32_e32 v70, v70
	v_add_f32_e32 v68, 1.0, v68
	v_add_f32_e32 v69, 1.0, v69
	v_rcp_f32_e32 v68, v68
	v_rcp_f32_e32 v69, v69
	v_pk_mul_f32 v[62:63], v[62:63], v[70:71]
	v_pk_mul_f32 v[64:65], v[64:65], v[68:69]
	v_cvt_pk_bf16_f32 v62, v62, v63
	v_cvt_pk_bf16_f32 v63, v64, v65
	v_lshl_add_u64 v[64:65], v[66:67], 0, v[0:1]
	s_waitcnt vmcnt(2)
	v_mov_b64_e32 v[64:65], v[190:191]
	s_add_u32 s86, s86, 0x2a300
	s_addc_u32 s87, s87, 0
	global_load_dwordx2 v[190:191], v163, s[86:87]
	v_lshlrev_b32_e32 v68, 16, v64
	v_and_b32_e32 v64, 0xffff0000, v64
	v_mul_f32_e32 v64, 0xbfb8aa3b, v64
	v_exp_f32_e32 v64, v64
	v_mul_f32_e32 v68, 0xbfb8aa3b, v68
	v_exp_f32_e32 v68, v68
	v_add_f32_e32 v64, 1.0, v64
	v_rcp_f32_e32 v69, v64
	v_lshlrev_b32_e32 v64, 16, v65
	v_and_b32_e32 v65, 0xffff0000, v65
	v_mul_f32_e32 v64, 0xbfb8aa3b, v64
	v_mul_f32_e32 v65, 0xbfb8aa3b, v65
	v_exp_f32_e32 v64, v64
	v_exp_f32_e32 v65, v65
	v_add_f32_e32 v68, 1.0, v68
	v_rcp_f32_e32 v68, v68
	v_add_f32_e32 v64, 1.0, v64
	v_add_f32_e32 v65, 1.0, v65
	v_rcp_f32_e32 v64, v64
	v_rcp_f32_e32 v65, v65
	v_pk_mul_f32 v[58:59], v[58:59], v[68:69]
	v_pk_mul_f32 v[60:61], v[60:61], v[64:65]
	v_cvt_pk_bf16_f32 v58, v58, v59
	v_cvt_pk_bf16_f32 v59, v60, v61
	v_add_u32_e32 v64, 0x8000, v138
	ds_write2_b64 v64, v[62:63], v[58:59] offset0:128 offset1:132
	v_lshl_add_u64 v[58:59], v[66:67], 0, v[122:123]
	s_waitcnt vmcnt(2)
; DI float bflo(unsigned u) { return __uint_as_float(u << 16); }
; DI float bfhi(unsigned u) { return __uint_as_float(u & 0xffff0000u); }
; DI float sigmoidf(float x) { return __builtin_amdgcn_rcpf(1.f + __expf(-x)); }
; template <class F>
; DI void gemm8_epi_staged(f32x4 (&acc)[8][4], int m0, int n0, bf16_t* L0, F f, bf16_t* dst, size_t ld, int nmax) {
;     ...
;     if (wm == half) {
; #pragma unroll
;       for (int i = 0; i < 8; ++i)
; #pragma unroll
;         for (int j = 0; j < 4; ++j) {
;           const int ml = i * 16 + (lane & 15);
;           const int nl = wn * 64 + j * 16 + (lane >> 4) * 4;
;           f32x4 a = acc[i][j];
;           f(m0 + half * 128 + ml, n0 + nl, a);
;           uint2 u;
;           u.x = pack2(a[0], a[1]);
;           u.y = pack2(a[2], a[3]);
;           *(uint2*)(L + ml * 264 + nl) = u;
;         }
;     }
; __global__ void __launch_bounds__(512, 2) mega(Params p) {
;     ...
;       gemm8_epi_staged(acc8, m0, n0, lds_all, [&](int m, int n, f32x4& a) {
;         uint2 ub = *(const uint2*)(z + (size_t)m * ZS + C_MB + n);
;         a[0] *= sigmoidf(bflo(ub.x)); a[1] *= sigmoidf(bfhi(ub.x));
;         a[2] *= sigmoidf(bflo(ub.y)); a[3] *= sigmoidf(bfhi(ub.y));
;       }, z + C_RK, ZS, 1024);
	v_mov_b64_e32 v[58:59], v[160:161]
	global_load_dwordx2 v[160:161], v163, s[86:87] offset:32
	v_lshlrev_b32_e32 v60, 16, v58
	v_and_b32_e32 v58, 0xffff0000, v58
	v_mul_f32_e32 v58, 0xbfb8aa3b, v58
	v_exp_f32_e32 v58, v58
	v_mul_f32_e32 v60, 0xbfb8aa3b, v60
	v_exp_f32_e32 v60, v60
	v_add_f32_e32 v58, 1.0, v58
	v_rcp_f32_e32 v61, v58
	v_lshlrev_b32_e32 v58, 16, v59
	v_and_b32_e32 v59, 0xffff0000, v59
	v_mul_f32_e32 v58, 0xbfb8aa3b, v58
	v_mul_f32_e32 v59, 0xbfb8aa3b, v59
	v_exp_f32_e32 v58, v58
	v_exp_f32_e32 v59, v59
	v_add_f32_e32 v60, 1.0, v60
	v_rcp_f32_e32 v60, v60
	v_add_f32_e32 v58, 1.0, v58
	v_add_f32_e32 v59, 1.0, v59
	v_rcp_f32_e32 v58, v58
	v_rcp_f32_e32 v59, v59
	v_pk_mul_f32 v[54:55], v[54:55], v[60:61]
	v_pk_mul_f32 v[56:57], v[56:57], v[58:59]
	v_cvt_pk_bf16_f32 v54, v54, v55
	v_cvt_pk_bf16_f32 v55, v56, v57
	v_lshl_add_u64 v[56:57], v[66:67], 0, v[118:119]
	s_waitcnt vmcnt(2)
	v_mov_b64_e32 v[56:57], v[188:189]
	global_load_dwordx2 v[188:189], v163, s[86:87] offset:64
	v_lshlrev_b32_e32 v58, 16, v56
	v_and_b32_e32 v56, 0xffff0000, v56
	v_mul_f32_e32 v56, 0xbfb8aa3b, v56
	v_exp_f32_e32 v56, v56
	v_mul_f32_e32 v58, 0xbfb8aa3b, v58
	v_exp_f32_e32 v58, v58
	v_add_f32_e32 v56, 1.0, v56
	v_rcp_f32_e32 v59, v56
	v_lshlrev_b32_e32 v56, 16, v57
	v_and_b32_e32 v57, 0xffff0000, v57
	v_mul_f32_e32 v56, 0xbfb8aa3b, v56
	v_mul_f32_e32 v57, 0xbfb8aa3b, v57
	v_exp_f32_e32 v56, v56
	v_exp_f32_e32 v57, v57
	v_add_f32_e32 v58, 1.0, v58
	v_rcp_f32_e32 v58, v58
	v_add_f32_e32 v56, 1.0, v56
	v_add_f32_e32 v57, 1.0, v57
	v_rcp_f32_e32 v56, v56
	v_rcp_f32_e32 v57, v57
	v_pk_mul_f32 v[50:51], v[50:51], v[58:59]
	v_pk_mul_f32 v[52:53], v[52:53], v[56:57]
	v_cvt_pk_bf16_f32 v50, v50, v51
	v_cvt_pk_bf16_f32 v51, v52, v53
	ds_write2_b64 v64, v[54:55], v[50:51] offset0:136 offset1:140
	v_or_b32_e32 v50, 0x50, v139
	v_mul_u32_u24_e32 v50, 0x2a30, v50
	v_mov_b32_e32 v51, v1
	v_lshl_add_u64 v[50:51], s[16:17], 0, v[50:51]
	v_lshl_add_u64 v[50:51], v[50:51], 0, s[6:7]
	v_lshl_add_u64 v[52:53], v[50:51], 0, v[130:131]
	s_waitcnt vmcnt(2)
	v_mov_b64_e32 v[52:53], v[190:191]
	global_load_dwordx2 v[190:191], v163, s[86:87] offset:96
	v_lshlrev_b32_e32 v54, 16, v52
	v_and_b32_e32 v52, 0xffff0000, v52
	v_mul_f32_e32 v52, 0xbfb8aa3b, v52
	v_exp_f32_e32 v52, v52
	v_mul_f32_e32 v54, 0xbfb8aa3b, v54
	v_exp_f32_e32 v54, v54
	v_add_f32_e32 v52, 1.0, v52
	v_rcp_f32_e32 v55, v52
	v_lshlrev_b32_e32 v52, 16, v53
	v_and_b32_e32 v53, 0xffff0000, v53
	v_mul_f32_e32 v52, 0xbfb8aa3b, v52
	v_mul_f32_e32 v53, 0xbfb8aa3b, v53
	v_exp_f32_e32 v52, v52
	v_exp_f32_e32 v53, v53
	v_add_f32_e32 v54, 1.0, v54
	v_rcp_f32_e32 v54, v54
	v_add_f32_e32 v52, 1.0, v52
	v_add_f32_e32 v53, 1.0, v53
	v_rcp_f32_e32 v52, v52
	v_rcp_f32_e32 v53, v53
	v_pk_mul_f32 v[46:47], v[46:47], v[54:55]
	v_pk_mul_f32 v[48:49], v[48:49], v[52:53]
	v_cvt_pk_bf16_f32 v46, v46, v47
	v_cvt_pk_bf16_f32 v47, v48, v49
	v_lshl_add_u64 v[48:49], v[50:51], 0, v[0:1]
	s_waitcnt vmcnt(2)
	v_mov_b64_e32 v[48:49], v[160:161]
	s_add_u32 s86, s86, 0x2a300
	s_addc_u32 s87, s87, 0
	global_load_dwordx2 v[160:161], v163, s[86:87]
	v_lshlrev_b32_e32 v52, 16, v48
	v_and_b32_e32 v48, 0xffff0000, v48
	v_mul_f32_e32 v48, 0xbfb8aa3b, v48
	v_exp_f32_e32 v48, v48
	v_mul_f32_e32 v52, 0xbfb8aa3b, v52
	v_exp_f32_e32 v52, v52
	v_add_f32_e32 v48, 1.0, v48
	v_rcp_f32_e32 v53, v48
	v_lshlrev_b32_e32 v48, 16, v49
	v_and_b32_e32 v49, 0xffff0000, v49
	v_mul_f32_e32 v48, 0xbfb8aa3b, v48
	v_mul_f32_e32 v49, 0xbfb8aa3b, v49
	v_exp_f32_e32 v48, v48
	v_exp_f32_e32 v49, v49
	v_add_f32_e32 v52, 1.0, v52
	v_rcp_f32_e32 v52, v52
	v_add_f32_e32 v48, 1.0, v48
	v_add_f32_e32 v49, 1.0, v49
	v_rcp_f32_e32 v48, v48
	v_rcp_f32_e32 v49, v49
	v_pk_mul_f32 v[42:43], v[42:43], v[52:53]
	v_pk_mul_f32 v[44:45], v[44:45], v[48:49]
	v_cvt_pk_bf16_f32 v42, v42, v43
	v_cvt_pk_bf16_f32 v43, v44, v45
	v_add_u32_e32 v48, 0xa000, v138
	ds_write2_b64 v48, v[46:47], v[42:43] offset0:160 offset1:164
	v_lshl_add_u64 v[42:43], v[50:51], 0, v[122:123]
	s_waitcnt vmcnt(2)
	v_mov_b64_e32 v[42:43], v[188:189]
	global_load_dwordx2 v[188:189], v163, s[86:87] offset:32
	v_lshlrev_b32_e32 v44, 16, v42
	v_and_b32_e32 v42, 0xffff0000, v42
	v_mul_f32_e32 v42, 0xbfb8aa3b, v42
	v_exp_f32_e32 v42, v42
	v_mul_f32_e32 v44, 0xbfb8aa3b, v44
	v_exp_f32_e32 v44, v44
	v_add_f32_e32 v42, 1.0, v42
	v_rcp_f32_e32 v45, v42
	v_lshlrev_b32_e32 v42, 16, v43
	v_and_b32_e32 v43, 0xffff0000, v43
	v_mul_f32_e32 v42, 0xbfb8aa3b, v42
	v_mul_f32_e32 v43, 0xbfb8aa3b, v43
	v_exp_f32_e32 v42, v42
	v_exp_f32_e32 v43, v43
	v_add_f32_e32 v44, 1.0, v44
	v_rcp_f32_e32 v44, v44
	v_add_f32_e32 v42, 1.0, v42
	v_add_f32_e32 v43, 1.0, v43
	v_rcp_f32_e32 v42, v42
	v_rcp_f32_e32 v43, v43
	v_pk_mul_f32 v[38:39], v[38:39], v[44:45]
	v_pk_mul_f32 v[40:41], v[40:41], v[42:43]
	v_cvt_pk_bf16_f32 v38, v38, v39
	v_cvt_pk_bf16_f32 v39, v40, v41
	v_lshl_add_u64 v[40:41], v[50:51], 0, v[118:119]
	s_waitcnt vmcnt(2)
	v_mov_b64_e32 v[40:41], v[190:191]
	global_load_dwordx2 v[190:191], v163, s[86:87] offset:64
	v_lshlrev_b32_e32 v42, 16, v40
	v_and_b32_e32 v40, 0xffff0000, v40
	v_mul_f32_e32 v40, 0xbfb8aa3b, v40
	v_exp_f32_e32 v40, v40
	v_mul_f32_e32 v42, 0xbfb8aa3b, v42
	v_exp_f32_e32 v42, v42
	v_add_f32_e32 v40, 1.0, v40
	v_rcp_f32_e32 v43, v40
	v_lshlrev_b32_e32 v40, 16, v41
	v_and_b32_e32 v41, 0xffff0000, v41
	v_mul_f32_e32 v40, 0xbfb8aa3b, v40
	v_mul_f32_e32 v41, 0xbfb8aa3b, v41
	v_exp_f32_e32 v40, v40
	v_exp_f32_e32 v41, v41
	v_add_f32_e32 v42, 1.0, v42
	v_rcp_f32_e32 v42, v42
	v_add_f32_e32 v40, 1.0, v40
	v_add_f32_e32 v41, 1.0, v41
	v_rcp_f32_e32 v40, v40
	v_rcp_f32_e32 v41, v41
	v_pk_mul_f32 v[34:35], v[34:35], v[42:43]
	v_pk_mul_f32 v[36:37], v[36:37], v[40:41]
	v_cvt_pk_bf16_f32 v34, v34, v35
	v_cvt_pk_bf16_f32 v35, v36, v37
	ds_write2_b64 v48, v[38:39], v[34:35] offset0:168 offset1:172
	v_or_b32_e32 v34, 0x60, v139
	v_mul_u32_u24_e32 v34, 0x2a30, v34
	v_mov_b32_e32 v35, v1
	v_lshl_add_u64 v[34:35], s[16:17], 0, v[34:35]
	v_lshl_add_u64 v[34:35], v[34:35], 0, s[6:7]
	v_lshl_add_u64 v[36:37], v[34:35], 0, v[130:131]
	s_waitcnt vmcnt(2)
; DI float bflo(unsigned u) { return __uint_as_float(u << 16); }
; DI float bfhi(unsigned u) { return __uint_as_float(u & 0xffff0000u); }
; DI float sigmoidf(float x) { return __builtin_amdgcn_rcpf(1.f + __expf(-x)); }
; template <class F>
; DI void gemm8_epi_staged(f32x4 (&acc)[8][4], int m0, int n0, bf16_t* L0, F f, bf16_t* dst, size_t ld, int nmax) {
;     ...
;       for (int i = 0; i < 8; ++i)
; #pragma unroll
;         for (int j = 0; j < 4; ++j) {
;           const int ml = i * 16 + (lane & 15);
;           const int nl = wn * 64 + j * 16 + (lane >> 4) * 4;
;           f32x4 a = acc[i][j];
;           f(m0 + half * 128 + ml, n0 + nl, a);
;           uint2 u;
;           u.x = pack2(a[0], a[1]);
;           u.y = pack2(a[2], a[3]);
;           *(uint2*)(L + ml * 264 + nl) = u;
;         }
; __global__ void __launch_bounds__(512, 2) mega(Params p) {
;     ...
;       gemm8_epi_staged(acc8, m0, n0, lds_all, [&](int m, int n, f32x4& a) {
;         uint2 ub = *(const uint2*)(z + (size_t)m * ZS + C_MB + n);
;         a[0] *= sigmoidf(bflo(ub.x)); a[1] *= sigmoidf(bfhi(ub.x));
;         a[2] *= sigmoidf(bflo(ub.y)); a[3] *= sigmoidf(bfhi(ub.y));
;       }, z + C_RK, ZS, 1024);
	v_mov_b64_e32 v[36:37], v[160:161]
	global_load_dwordx2 v[160:161], v163, s[86:87] offset:96
	v_lshlrev_b32_e32 v38, 16, v36
	v_and_b32_e32 v36, 0xffff0000, v36
	v_mul_f32_e32 v36, 0xbfb8aa3b, v36
	v_exp_f32_e32 v36, v36
	v_mul_f32_e32 v38, 0xbfb8aa3b, v38
	v_exp_f32_e32 v38, v38
	v_add_f32_e32 v36, 1.0, v36
	v_rcp_f32_e32 v39, v36
	v_lshlrev_b32_e32 v36, 16, v37
	v_and_b32_e32 v37, 0xffff0000, v37
	v_mul_f32_e32 v36, 0xbfb8aa3b, v36
	v_mul_f32_e32 v37, 0xbfb8aa3b, v37
	v_exp_f32_e32 v36, v36
	v_exp_f32_e32 v37, v37
	v_add_f32_e32 v38, 1.0, v38
	v_rcp_f32_e32 v38, v38
	v_add_f32_e32 v36, 1.0, v36
	v_add_f32_e32 v37, 1.0, v37
	v_rcp_f32_e32 v36, v36
	v_rcp_f32_e32 v37, v37
	v_pk_mul_f32 v[30:31], v[30:31], v[38:39]
	v_pk_mul_f32 v[32:33], v[32:33], v[36:37]
	v_cvt_pk_bf16_f32 v30, v30, v31
	v_cvt_pk_bf16_f32 v31, v32, v33
	v_lshl_add_u64 v[32:33], v[34:35], 0, v[0:1]
	s_waitcnt vmcnt(2)
	v_mov_b64_e32 v[32:33], v[188:189]
	s_add_u32 s86, s86, 0x2a300
	s_addc_u32 s87, s87, 0
	global_load_dwordx2 v[188:189], v163, s[86:87]
	v_lshlrev_b32_e32 v36, 16, v32
	v_and_b32_e32 v32, 0xffff0000, v32
	v_mul_f32_e32 v32, 0xbfb8aa3b, v32
	v_exp_f32_e32 v32, v32
	v_mul_f32_e32 v36, 0xbfb8aa3b, v36
	v_exp_f32_e32 v36, v36
	v_add_f32_e32 v32, 1.0, v32
	v_rcp_f32_e32 v37, v32
	v_lshlrev_b32_e32 v32, 16, v33
	v_and_b32_e32 v33, 0xffff0000, v33
	v_mul_f32_e32 v32, 0xbfb8aa3b, v32
	v_mul_f32_e32 v33, 0xbfb8aa3b, v33
	v_exp_f32_e32 v32, v32
	v_exp_f32_e32 v33, v33
	v_add_f32_e32 v36, 1.0, v36
	v_rcp_f32_e32 v36, v36
	v_add_f32_e32 v32, 1.0, v32
	v_add_f32_e32 v33, 1.0, v33
	v_rcp_f32_e32 v32, v32
	v_rcp_f32_e32 v33, v33
	v_pk_mul_f32 v[26:27], v[26:27], v[36:37]
	v_pk_mul_f32 v[28:29], v[28:29], v[32:33]
	v_cvt_pk_bf16_f32 v26, v26, v27
	v_cvt_pk_bf16_f32 v27, v28, v29
	v_add_u32_e32 v32, 0xc000, v138
	ds_write2_b64 v32, v[30:31], v[26:27] offset0:192 offset1:196
	v_lshl_add_u64 v[26:27], v[34:35], 0, v[122:123]
	s_waitcnt vmcnt(2)
	v_mov_b64_e32 v[26:27], v[190:191]
	global_load_dwordx2 v[190:191], v163, s[86:87] offset:32
	v_lshlrev_b32_e32 v28, 16, v26
	v_and_b32_e32 v26, 0xffff0000, v26
	v_mul_f32_e32 v26, 0xbfb8aa3b, v26
	v_exp_f32_e32 v26, v26
	v_mul_f32_e32 v28, 0xbfb8aa3b, v28
	v_exp_f32_e32 v28, v28
	v_add_f32_e32 v26, 1.0, v26
	v_rcp_f32_e32 v29, v26
	v_lshlrev_b32_e32 v26, 16, v27
	v_and_b32_e32 v27, 0xffff0000, v27
	v_mul_f32_e32 v26, 0xbfb8aa3b, v26
	v_mul_f32_e32 v27, 0xbfb8aa3b, v27
	v_exp_f32_e32 v26, v26
	v_exp_f32_e32 v27, v27
	v_add_f32_e32 v28, 1.0, v28
	v_rcp_f32_e32 v28, v28
	v_add_f32_e32 v26, 1.0, v26
	v_add_f32_e32 v27, 1.0, v27
	v_rcp_f32_e32 v26, v26
	v_rcp_f32_e32 v27, v27
	v_pk_mul_f32 v[22:23], v[22:23], v[28:29]
	v_pk_mul_f32 v[24:25], v[24:25], v[26:27]
	v_cvt_pk_bf16_f32 v22, v22, v23
	v_cvt_pk_bf16_f32 v23, v24, v25
	v_lshl_add_u64 v[24:25], v[34:35], 0, v[118:119]
	s_waitcnt vmcnt(2)
	v_mov_b64_e32 v[24:25], v[160:161]
	global_load_dwordx2 v[160:161], v163, s[86:87] offset:64
	v_lshlrev_b32_e32 v26, 16, v24
	v_and_b32_e32 v24, 0xffff0000, v24
	v_mul_f32_e32 v24, 0xbfb8aa3b, v24
	v_exp_f32_e32 v24, v24
	v_mul_f32_e32 v26, 0xbfb8aa3b, v26
	v_exp_f32_e32 v26, v26
	v_add_f32_e32 v24, 1.0, v24
	v_rcp_f32_e32 v27, v24
	v_lshlrev_b32_e32 v24, 16, v25
	v_and_b32_e32 v25, 0xffff0000, v25
	v_mul_f32_e32 v24, 0xbfb8aa3b, v24
	v_mul_f32_e32 v25, 0xbfb8aa3b, v25
	v_exp_f32_e32 v24, v24
	v_exp_f32_e32 v25, v25
	v_add_f32_e32 v26, 1.0, v26
	v_rcp_f32_e32 v26, v26
	v_add_f32_e32 v24, 1.0, v24
	v_add_f32_e32 v25, 1.0, v25
	v_rcp_f32_e32 v24, v24
	v_rcp_f32_e32 v25, v25
	v_pk_mul_f32 v[18:19], v[18:19], v[26:27]
	v_pk_mul_f32 v[20:21], v[20:21], v[24:25]
	v_cvt_pk_bf16_f32 v18, v18, v19
	v_cvt_pk_bf16_f32 v19, v20, v21
	ds_write2_b64 v32, v[22:23], v[18:19] offset0:200 offset1:204
	v_or_b32_e32 v18, 0x70, v139
	v_mul_u32_u24_e32 v18, 0x2a30, v18
	v_mov_b32_e32 v19, v1
	v_lshl_add_u64 v[18:19], s[16:17], 0, v[18:19]
	v_lshl_add_u64 v[18:19], v[18:19], 0, s[6:7]
	v_lshl_add_u64 v[20:21], v[18:19], 0, v[130:131]
	s_waitcnt vmcnt(2)
; DI float bflo(unsigned u) { return __uint_as_float(u << 16); }
; DI float bfhi(unsigned u) { return __uint_as_float(u & 0xffff0000u); }
; DI float sigmoidf(float x) { return __builtin_amdgcn_rcpf(1.f + __expf(-x)); }
; template <class F>
; DI void gemm8_epi_staged(f32x4 (&acc)[8][4], int m0, int n0, bf16_t* L0, F f, bf16_t* dst, size_t ld, int nmax) {
;     ...
;       for (int i = 0; i < 8; ++i)
; #pragma unroll
;         for (int j = 0; j < 4; ++j) {
;           const int ml = i * 16 + (lane & 15);
;           const int nl = wn * 64 + j * 16 + (lane >> 4) * 4;
;           f32x4 a = acc[i][j];
;           f(m0 + half * 128 + ml, n0 + nl, a);
;           uint2 u;
;           u.x = pack2(a[0], a[1]);
;           u.y = pack2(a[2], a[3]);
;           *(uint2*)(L + ml * 264 + nl) = u;
;         }
; __global__ void __launch_bounds__(512, 2) mega(Params p) {
;     ...
;       gemm8_epi_staged(acc8, m0, n0, lds_all, [&](int m, int n, f32x4& a) {
;         uint2 ub = *(const uint2*)(z + (size_t)m * ZS + C_MB + n);
;         a[0] *= sigmoidf(bflo(ub.x)); a[1] *= sigmoidf(bfhi(ub.x));
;         a[2] *= sigmoidf(bflo(ub.y)); a[3] *= sigmoidf(bfhi(ub.y));
;       }, z + C_RK, ZS, 1024);
	v_mov_b64_e32 v[20:21], v[188:189]
	global_load_dwordx2 v[188:189], v163, s[86:87] offset:96
	v_lshlrev_b32_e32 v22, 16, v20
	v_and_b32_e32 v20, 0xffff0000, v20
	v_mul_f32_e32 v20, 0xbfb8aa3b, v20
	v_exp_f32_e32 v20, v20
	v_mul_f32_e32 v22, 0xbfb8aa3b, v22
	v_exp_f32_e32 v22, v22
	v_add_f32_e32 v20, 1.0, v20
	v_rcp_f32_e32 v23, v20
	v_lshlrev_b32_e32 v20, 16, v21
	v_and_b32_e32 v21, 0xffff0000, v21
	v_mul_f32_e32 v20, 0xbfb8aa3b, v20
	v_mul_f32_e32 v21, 0xbfb8aa3b, v21
	v_exp_f32_e32 v20, v20
	v_exp_f32_e32 v21, v21
	v_add_f32_e32 v22, 1.0, v22
	v_rcp_f32_e32 v22, v22
	v_add_f32_e32 v20, 1.0, v20
	v_add_f32_e32 v21, 1.0, v21
	v_rcp_f32_e32 v20, v20
	v_rcp_f32_e32 v21, v21
	v_pk_mul_f32 v[14:15], v[14:15], v[22:23]
	v_pk_mul_f32 v[16:17], v[16:17], v[20:21]
	v_cvt_pk_bf16_f32 v14, v14, v15
	v_cvt_pk_bf16_f32 v15, v16, v17
	v_lshl_add_u64 v[16:17], v[18:19], 0, v[0:1]
	s_waitcnt vmcnt(2)
	v_mov_b64_e32 v[16:17], v[190:191]
	v_lshlrev_b32_e32 v0, 16, v16
	v_mul_f32_e32 v0, 0xbfb8aa3b, v0
	v_exp_f32_e32 v0, v0
	s_nop 0
	v_add_f32_e32 v0, 1.0, v0
	v_rcp_f32_e32 v20, v0
	v_and_b32_e32 v0, 0xffff0000, v16
	v_mul_f32_e32 v0, 0xbfb8aa3b, v0
	v_exp_f32_e32 v0, v0
	s_nop 0
	v_add_f32_e32 v0, 1.0, v0
	v_rcp_f32_e32 v21, v0
	v_lshlrev_b32_e32 v0, 16, v17
	v_mul_f32_e32 v0, 0xbfb8aa3b, v0
	v_exp_f32_e32 v0, v0
	v_pk_mul_f32 v[10:11], v[10:11], v[20:21]
	v_add_f32_e32 v0, 1.0, v0
	v_rcp_f32_e32 v16, v0
	v_and_b32_e32 v0, 0xffff0000, v17
	v_mul_f32_e32 v0, 0xbfb8aa3b, v0
	v_exp_f32_e32 v0, v0
	v_cvt_pk_bf16_f32 v10, v10, v11
	v_add_f32_e32 v0, 1.0, v0
	v_rcp_f32_e32 v17, v0
	v_add_u32_e32 v0, 0xe000, v138
	v_pk_mul_f32 v[12:13], v[12:13], v[16:17]
	s_nop 0
	v_cvt_pk_bf16_f32 v11, v12, v13
	ds_write2_b64 v0, v[14:15], v[10:11] offset0:224 offset1:228
	v_lshl_add_u64 v[10:11], v[18:19], 0, v[122:123]
	s_waitcnt vmcnt(1)
	v_mov_b64_e32 v[10:11], v[160:161]
	v_lshlrev_b32_e32 v12, 16, v10
	v_and_b32_e32 v10, 0xffff0000, v10
	v_mul_f32_e32 v10, 0xbfb8aa3b, v10
	v_exp_f32_e32 v10, v10
	v_mul_f32_e32 v12, 0xbfb8aa3b, v12
	v_exp_f32_e32 v12, v12
	v_add_f32_e32 v10, 1.0, v10
	v_rcp_f32_e32 v13, v10
	v_lshlrev_b32_e32 v10, 16, v11
	v_and_b32_e32 v11, 0xffff0000, v11
	v_mul_f32_e32 v10, 0xbfb8aa3b, v10
	v_mul_f32_e32 v11, 0xbfb8aa3b, v11
	v_exp_f32_e32 v10, v10
	v_exp_f32_e32 v11, v11
	v_add_f32_e32 v12, 1.0, v12
	v_rcp_f32_e32 v12, v12
	v_add_f32_e32 v10, 1.0, v10
	v_add_f32_e32 v11, 1.0, v11
	v_rcp_f32_e32 v10, v10
	v_rcp_f32_e32 v11, v11
	v_pk_mul_f32 v[6:7], v[6:7], v[12:13]
	v_pk_mul_f32 v[8:9], v[8:9], v[10:11]
	v_cvt_pk_bf16_f32 v6, v6, v7
	v_cvt_pk_bf16_f32 v7, v8, v9
	v_lshl_add_u64 v[8:9], v[18:19], 0, v[118:119]
	s_waitcnt vmcnt(0)
	v_mov_b64_e32 v[8:9], v[188:189]
	v_lshlrev_b32_e32 v10, 16, v8
	v_and_b32_e32 v8, 0xffff0000, v8
	v_mul_f32_e32 v8, 0xbfb8aa3b, v8
	v_exp_f32_e32 v8, v8
	v_mul_f32_e32 v10, 0xbfb8aa3b, v10
	v_exp_f32_e32 v10, v10
	v_add_f32_e32 v8, 1.0, v8
	v_rcp_f32_e32 v11, v8
	v_lshlrev_b32_e32 v8, 16, v9
	v_and_b32_e32 v9, 0xffff0000, v9
	v_mul_f32_e32 v8, 0xbfb8aa3b, v8
	v_mul_f32_e32 v9, 0xbfb8aa3b, v9
	v_exp_f32_e32 v8, v8
	v_exp_f32_e32 v9, v9
	v_add_f32_e32 v10, 1.0, v10
	v_rcp_f32_e32 v10, v10
	v_add_f32_e32 v8, 1.0, v8
	v_add_f32_e32 v9, 1.0, v9
	v_rcp_f32_e32 v8, v8
	v_rcp_f32_e32 v9, v9
	v_pk_mul_f32 v[2:3], v[2:3], v[10:11]
	v_pk_mul_f32 v[4:5], v[4:5], v[8:9]
	v_cvt_pk_bf16_f32 v2, v2, v3
	v_cvt_pk_bf16_f32 v3, v4, v5
	ds_write2_b64 v0, v[6:7], v[2:3] offset0:232 offset1:236
	s_branch .LBB0_772
